# G1 GQA-tile epilogue: rotary table loads issued one row ahead with counted vmcnt
# speedup vs baseline: 1.0302x; 1.0042x over previous
; DI u32x4 pk8(const f32x4& a, const f32x4& b) { u32x4 w; w.x = pk2(a[0], a[1]); w.y = pk2(a[2], a[3]); w.z = pk2(b[0], b[1]); w.w = pk2(b[2], b[3]); return w; }
; DI float shx(float v, int m, int lane) { return __int_as_float(__builtin_amdgcn_ds_bpermute((lane ^ m) << 2, __float_as_int(v))); }
; #define FOR_AI_M _Pragma("unroll") for (int ai = 0; ai < 2; ++ai) _Pragma("unroll") for (int m = 0; m < 4; ++m)
;     DI void operator()(Acc& acc, const Unit& u, int wr, int wc, int fr, int fq) const {
;     ...
;         FOR_AI_M { const int r = row0 + EPI_ROWS(ai, m);
;             f32x4 x[2][2];
; #pragma unroll
;             for (int bj = 0; bj < 2; ++bj) { x[bj][0] = acc[ai][bj][m][0]; x[bj][1] = acc[ai][bj][m][1]; }
;             if (!is_v) {
;                 float s = 0.f;
; #pragma unroll
;                 for (int bj = 0; bj < 2; ++bj)
; #pragma unroll
;                     for (int n = 0; n < 2; ++n) s += (x[bj][n][0] * x[bj][n][0] + x[bj][n][1] * x[bj][n][1]) + (x[bj][n][2] * x[bj][n][2] + x[bj][n][3] * x[bj][n][3]);
;                 s += shx(s, 16, fr + 16 * fq); s += shx(s, 32, fr + 16 * fq);
;                 const float rstd = 1.f / sqrtf(s * (1.f / 64.f) + EPS);
; #pragma unroll
;                 for (int bj = 0; bj < 2; ++bj)
; #pragma unroll
;                     for (int n = 0; n < 2; ++n) x[bj][n] = x[bj][n] * rstd * gv[bj][n];
;                 if (rope) {
;                     const float* rr = rg + (size_t)(r & 2047) * 64 + 8 * fq;
; #pragma unroll
;                     for (int n = 0; n < 2; ++n) { const f32x4 cs = *(const f32x4*)(rr + 4 * n), sn = *(const f32x4*)(rr + 32 + 4 * n);
;                         const f32x4 x1 = x[0][n], x2 = x[1][n]; x[0][n] = x1 * cs - x2 * sn; x[1][n] = x1 * sn + x2 * cs; }
;                 }
; #pragma unroll
;                 for (int bj = 0; bj < 2; ++bj)
; #pragma unroll
;                     for (int n = 0; n < 2; ++n) x[bj][n] = x[bj][n] * qs;
;             }
; #pragma unroll
;             for (int bj = 0; bj < 2; ++bj) *(u32x4*)(dst + (size_t)r * ld + colb + 32 * bj + 8 * fq) = pk8(x[bj][0], x[bj][1]);
.LBB0_607:
	s_xor_b64 s[10:11], s[34:35], -1
	s_add_u32 s12, s94, s12
	s_addc_u32 s13, s95, s13
	s_lshl_b64 s[8:9], s[16:17], 1
	s_add_u32 s8, s12, s8
	s_addc_u32 s9, s13, s9
	v_lshlrev_b32_e32 v96, 1, v172
	v_lshl_add_u64 v[98:99], s[8:9], 0, v[96:97]
	v_mad_i64_i32 v[192:193], s[8:9], s42, v199, 0
	v_lshl_add_u64 v[192:193], v[192:193], 1, v[98:99]
	v_cvt_pk_bf16_f32 v152, v152, v153
	v_cvt_pk_bf16_f32 v153, v154, v155
	v_cvt_pk_bf16_f32 v154, v148, v149
	v_cvt_pk_bf16_f32 v155, v150, v151
	v_cvt_pk_bf16_f32 v148, v156, v157
	v_cvt_pk_bf16_f32 v149, v158, v159
	v_cvt_pk_bf16_f32 v150, v160, v161
	v_cvt_pk_bf16_f32 v151, v162, v163
	v_lshlrev_b32_e32 v251, 8, v199
	v_and_b32_e32 v251, 0x7ff00, v251
	v_mov_b32_e32 v249, 0
	v_add_u32_e32 v248, 0x1000, v251
	v_lshl_add_u64 v[252:253], v[176:177], 0, v[248:249]
	global_load_dwordx4 v[202:205], v[252:253], off offset:16
	global_load_dwordx4 v[206:209], v[252:253], off
	global_load_dwordx4 v[226:229], v[252:253], off offset:144
	global_load_dwordx4 v[230:233], v[252:253], off offset:128
	global_store_dwordx4 v[192:193], v[152:155], off
	global_store_dwordx4 v[192:193], v[148:151], off offset:64
	v_cndmask_b32_e64 v96, 0, 1, s[10:11]
	v_mov_b64_e32 v[154:155], v[122:123]
	v_mov_b64_e32 v[150:151], v[114:115]
	v_mov_b64_e32 v[158:159], v[102:103]
	v_mov_b64_e32 v[162:163], v[90:91]
	v_or_b32_e32 v200, 16, v199
	v_cmp_ne_u32_e64 s[8:9], 1, v96
	s_andn2_b64 vcc, exec, s[10:11]
	v_mov_b64_e32 v[152:153], v[120:121]
	v_mov_b64_e32 v[148:149], v[112:113]
	v_mov_b64_e32 v[156:157], v[100:101]
	v_mov_b64_e32 v[160:161], v[88:89]
	s_cbranch_vccnz .LBB0_611
	v_pk_mul_f32 v[148:149], v[122:123], v[122:123]
	v_pk_mul_f32 v[150:151], v[120:121], v[120:121]
	v_mul_f32_e32 v96, v100, v100
	v_pk_mov_b32 v[152:153], v[150:151], v[148:149] op_sel:[1,0]
	v_mov_b32_e32 v151, v149
	v_pk_add_f32 v[148:149], v[152:153], v[150:151]
	v_pk_mul_f32 v[150:151], v[114:115], v[114:115]
	v_pk_mul_f32 v[152:153], v[112:113], v[112:113]
	v_pk_add_f32 v[148:149], v[148:149], v[148:149] op_sel_hi:[0,1]
	v_pk_mov_b32 v[154:155], v[152:153], v[150:151] op_sel:[1,0]
	v_mov_b32_e32 v153, v151
	v_pk_add_f32 v[150:151], v[154:155], v[152:153]
	v_pk_fma_f32 v[152:153], v[100:101], v[100:101], v[96:97] op_sel_hi:[1,1,0]
	v_mul_f32_e32 v96, v102, v102
	v_pk_add_f32 v[150:151], v[150:151], v[150:151] op_sel_hi:[0,1]
	v_pk_fma_f32 v[154:155], v[102:103], v[102:103], v[96:97] op_sel_hi:[1,1,0]
	v_mul_f32_e32 v152, v88, v88
	v_mul_f32_e32 v154, v89, v89
	v_mul_f32_e32 v150, v90, v90
	v_mul_f32_e32 v148, v91, v91
	v_pk_add_f32 v[152:153], v[152:153], v[154:155]
	v_pk_add_f32 v[148:149], v[150:151], v[148:149]
	s_nop 0
	v_pk_add_f32 v[148:149], v[152:153], v[148:149]
	s_nop 0
	v_add_f32_e32 v96, v148, v149
	ds_bpermute_b32 v148, v194, v96
	s_waitcnt lgkmcnt(0)
	v_add_f32_e32 v96, v96, v148
	ds_bpermute_b32 v148, v195, v96
	s_waitcnt lgkmcnt(0)
	v_add_f32_e32 v96, v96, v148
	v_fmamk_f32 v96, v96, 0x3c800000, v185
	v_mul_f32_e32 v148, 0x4f800000, v96
	v_cmp_gt_f32_e32 vcc, s65, v96
	s_nop 1
	v_cndmask_b32_e32 v96, v96, v148, vcc
	v_sqrt_f32_e32 v148, v96
	s_nop 0
	v_add_u32_e32 v149, -1, v148
	v_fma_f32 v150, -v149, v148, v96
	v_cmp_ge_f32_e64 s[12:13], 0, v150
	v_add_u32_e32 v150, 1, v148
	s_nop 0
	v_cndmask_b32_e64 v149, v148, v149, s[12:13]
	v_fma_f32 v148, -v150, v148, v96
	v_cmp_lt_f32_e64 s[12:13], 0, v148
	s_nop 1
	v_cndmask_b32_e64 v148, v149, v150, s[12:13]
	v_mul_f32_e32 v149, 0x37800000, v148
	v_cndmask_b32_e32 v148, v148, v149, vcc
	v_cmp_class_f32_e32 vcc, v96, v183
	s_nop 1
	v_cndmask_b32_e32 v96, v148, v96, vcc
	v_div_scale_f32 v148, s[10:11], v96, v96, 1.0
	v_rcp_f32_e32 v149, v148
	s_nop 0
	v_fma_f32 v150, -v148, v149, 1.0
	v_fmac_f32_e32 v149, v150, v149
	v_div_scale_f32 v150, vcc, 1.0, v96, 1.0
	v_mul_f32_e32 v151, v150, v149
	v_fma_f32 v152, -v148, v151, v150
	v_fmac_f32_e32 v151, v152, v149
	v_fma_f32 v148, -v148, v151, v150
	v_div_fmas_f32 v148, v148, v149, v151
	v_div_fixup_f32 v96, v148, v96, 1.0
	v_pk_mul_f32 v[148:149], v[120:121], v[96:97] op_sel_hi:[1,0]
	v_pk_mul_f32 v[150:151], v[122:123], v[96:97] op_sel_hi:[1,0]
	s_waitcnt vmcnt(2)
	v_pk_mul_f32 v[152:153], v[144:145], v[148:149]
	v_pk_mul_f32 v[154:155], v[146:147], v[150:151]
	v_pk_mul_f32 v[148:149], v[112:113], v[96:97] op_sel_hi:[1,0]
	v_pk_mul_f32 v[150:151], v[114:115], v[96:97] op_sel_hi:[1,0]
	v_pk_mul_f32 v[156:157], v[100:101], v[96:97] op_sel_hi:[1,0]
	v_pk_mul_f32 v[158:159], v[102:103], v[96:97] op_sel_hi:[1,0]
	v_pk_mul_f32 v[162:163], v[88:89], v[96:97] op_sel_hi:[1,0]
	v_pk_mul_f32 v[160:161], v[90:91], v[96:97] op_sel_hi:[1,0]
	v_pk_mul_f32 v[150:151], v[142:143], v[150:151]
	v_pk_mul_f32 v[148:149], v[140:141], v[148:149]
	v_pk_mul_f32 v[158:159], v[138:139], v[158:159]
	v_pk_mul_f32 v[156:157], v[136:137], v[156:157]
	v_pk_mul_f32 v[160:161], v[134:135], v[160:161]
	s_and_b64 vcc, exec, s[6:7]
	v_pk_mul_f32 v[192:193], v[132:133], v[162:163]
	s_cbranch_vccnz .LBB0_610
	v_pk_mul_f32 v[210:211], v[156:157], v[230:231]
	v_pk_mul_f32 v[162:163], v[158:159], v[232:233]
	v_pk_fma_f32 v[234:235], v[152:153], v[206:207], v[210:211] neg_lo:[0,0,1] neg_hi:[0,0,1]
	v_pk_mul_f32 v[152:153], v[152:153], v[230:231]
	v_pk_fma_f32 v[236:237], v[154:155], v[208:209], v[162:163] neg_lo:[0,0,1] neg_hi:[0,0,1]
	v_pk_mul_f32 v[154:155], v[154:155], v[232:233]
	v_pk_fma_f32 v[156:157], v[156:157], v[206:207], v[152:153]
	v_pk_mul_f32 v[152:153], v[160:161], v[228:229]
	v_pk_mul_f32 v[162:163], v[192:193], v[226:227]
	v_pk_fma_f32 v[158:159], v[158:159], v[208:209], v[154:155]
	v_pk_fma_f32 v[154:155], v[150:151], v[204:205], v[152:153] neg_lo:[0,0,1] neg_hi:[0,0,1]
	v_pk_fma_f32 v[152:153], v[148:149], v[202:203], v[162:163] neg_lo:[0,0,1] neg_hi:[0,0,1]
	v_pk_mul_f32 v[150:151], v[150:151], v[228:229]
	v_pk_mul_f32 v[148:149], v[148:149], v[226:227]
	v_pk_fma_f32 v[160:161], v[160:161], v[204:205], v[150:151]
	v_pk_fma_f32 v[192:193], v[192:193], v[202:203], v[148:149]
	v_mov_b64_e32 v[148:149], v[152:153]
	v_mov_b64_e32 v[150:151], v[154:155]
	v_mov_b64_e32 v[152:153], v[234:235]
	v_mov_b64_e32 v[154:155], v[236:237]

; DI u32x4 pk8(const f32x4& a, const f32x4& b) { u32x4 w; w.x = pk2(a[0], a[1]); w.y = pk2(a[2], a[3]); w.z = pk2(b[0], b[1]); w.w = pk2(b[2], b[3]); return w; }
; DI float shx(float v, int m, int lane) { return __int_as_float(__builtin_amdgcn_ds_bpermute((lane ^ m) << 2, __float_as_int(v))); }
; #define FOR_AI_M _Pragma("unroll") for (int ai = 0; ai < 2; ++ai) _Pragma("unroll") for (int m = 0; m < 4; ++m)
;     DI void operator()(Acc& acc, const Unit& u, int wr, int wc, int fr, int fq) const {
;     ...
;         FOR_AI_M { const int r = row0 + EPI_ROWS(ai, m);
;             f32x4 x[2][2];
; #pragma unroll
;             for (int bj = 0; bj < 2; ++bj) { x[bj][0] = acc[ai][bj][m][0]; x[bj][1] = acc[ai][bj][m][1]; }
;             if (!is_v) {
;                 float s = 0.f;
; #pragma unroll
;                 for (int bj = 0; bj < 2; ++bj)
; #pragma unroll
;                     for (int n = 0; n < 2; ++n) s += (x[bj][n][0] * x[bj][n][0] + x[bj][n][1] * x[bj][n][1]) + (x[bj][n][2] * x[bj][n][2] + x[bj][n][3] * x[bj][n][3]);
;                 s += shx(s, 16, fr + 16 * fq); s += shx(s, 32, fr + 16 * fq);
;                 const float rstd = 1.f / sqrtf(s * (1.f / 64.f) + EPS);
; #pragma unroll
;                 for (int bj = 0; bj < 2; ++bj)
; #pragma unroll
;                     for (int n = 0; n < 2; ++n) x[bj][n] = x[bj][n] * rstd * gv[bj][n];
;                 if (rope) {
;                     const float* rr = rg + (size_t)(r & 2047) * 64 + 8 * fq;
; #pragma unroll
;                     for (int n = 0; n < 2; ++n) { const f32x4 cs = *(const f32x4*)(rr + 4 * n), sn = *(const f32x4*)(rr + 32 + 4 * n);
;                         const f32x4 x1 = x[0][n], x2 = x[1][n]; x[0][n] = x1 * cs - x2 * sn; x[1][n] = x1 * sn + x2 * cs; }
;                 }
; #pragma unroll
;                 for (int bj = 0; bj < 2; ++bj)
; #pragma unroll
;                     for (int n = 0; n < 2; ++n) x[bj][n] = x[bj][n] * qs;
;             }
; #pragma unroll
;             for (int bj = 0; bj < 2; ++bj) *(u32x4*)(dst + (size_t)r * ld + colb + 32 * bj + 8 * fq) = pk8(x[bj][0], x[bj][1]);
.LBB0_611:
	v_mad_i64_i32 v[192:193], s[10:11], s42, v200, 0
	v_lshl_add_u64 v[192:193], v[192:193], 1, v[98:99]
	v_cvt_pk_bf16_f32 v152, v152, v153
	v_cvt_pk_bf16_f32 v153, v154, v155
	v_cvt_pk_bf16_f32 v154, v148, v149
	v_cvt_pk_bf16_f32 v155, v150, v151
	v_cvt_pk_bf16_f32 v148, v156, v157
	v_cvt_pk_bf16_f32 v149, v158, v159
	v_cvt_pk_bf16_f32 v150, v160, v161
	v_cvt_pk_bf16_f32 v151, v162, v163
	v_add_u32_e32 v248, 0x2000, v251
	v_lshl_add_u64 v[252:253], v[176:177], 0, v[248:249]
	global_load_dwordx4 v[202:205], v[252:253], off offset:16
	global_load_dwordx4 v[206:209], v[252:253], off
	global_load_dwordx4 v[226:229], v[252:253], off offset:144
	global_load_dwordx4 v[230:233], v[252:253], off offset:128
	global_store_dwordx4 v[192:193], v[152:155], off
	global_store_dwordx4 v[192:193], v[148:151], off offset:64
	v_mov_b64_e32 v[158:159], v[82:83]
	v_mov_b64_e32 v[154:155], v[106:107]
	v_mov_b64_e32 v[150:151], v[94:95]
	v_mov_b64_e32 v[162:163], v[74:75]
	v_or_b32_e32 v200, 32, v199
	s_and_b64 vcc, exec, s[8:9]
	v_mov_b64_e32 v[152:153], v[104:105]
	v_mov_b64_e32 v[148:149], v[92:93]
	v_mov_b64_e32 v[156:157], v[80:81]
	v_mov_b64_e32 v[160:161], v[72:73]
	s_cbranch_vccnz .LBB0_615
	v_pk_mul_f32 v[148:149], v[106:107], v[106:107]
	v_pk_mul_f32 v[150:151], v[104:105], v[104:105]
	v_mul_f32_e32 v96, v80, v80
	v_pk_mov_b32 v[152:153], v[150:151], v[148:149] op_sel:[1,0]
	v_mov_b32_e32 v151, v149
	v_pk_add_f32 v[148:149], v[152:153], v[150:151]
	v_pk_mul_f32 v[150:151], v[94:95], v[94:95]
	v_pk_mul_f32 v[152:153], v[92:93], v[92:93]
	v_pk_add_f32 v[148:149], v[148:149], v[148:149] op_sel_hi:[0,1]
	v_pk_mov_b32 v[154:155], v[152:153], v[150:151] op_sel:[1,0]
	v_mov_b32_e32 v153, v151
	v_pk_add_f32 v[150:151], v[154:155], v[152:153]
	v_pk_fma_f32 v[152:153], v[80:81], v[80:81], v[96:97] op_sel_hi:[1,1,0]
	v_mul_f32_e32 v96, v82, v82
	v_pk_add_f32 v[150:151], v[150:151], v[150:151] op_sel_hi:[0,1]
	v_pk_fma_f32 v[154:155], v[82:83], v[82:83], v[96:97] op_sel_hi:[1,1,0]
	v_mul_f32_e32 v152, v72, v72
	v_mul_f32_e32 v154, v73, v73
	v_mul_f32_e32 v150, v74, v74
	v_mul_f32_e32 v148, v75, v75
	v_pk_add_f32 v[152:153], v[152:153], v[154:155]
	v_pk_add_f32 v[148:149], v[150:151], v[148:149]
	s_nop 0
	v_pk_add_f32 v[148:149], v[152:153], v[148:149]
	s_nop 0
	v_add_f32_e32 v96, v148, v149
	ds_bpermute_b32 v148, v194, v96
	s_waitcnt lgkmcnt(0)
	v_add_f32_e32 v96, v96, v148
	ds_bpermute_b32 v148, v195, v96
	s_waitcnt lgkmcnt(0)
	v_add_f32_e32 v96, v96, v148
	v_fmamk_f32 v96, v96, 0x3c800000, v185
	v_mul_f32_e32 v148, 0x4f800000, v96
	v_cmp_gt_f32_e32 vcc, s65, v96
	s_nop 1
	v_cndmask_b32_e32 v96, v96, v148, vcc
	v_sqrt_f32_e32 v148, v96
	s_nop 0
	v_add_u32_e32 v149, -1, v148
	v_fma_f32 v150, -v149, v148, v96
	v_cmp_ge_f32_e64 s[12:13], 0, v150
	v_add_u32_e32 v150, 1, v148
	s_nop 0
	v_cndmask_b32_e64 v149, v148, v149, s[12:13]
	v_fma_f32 v148, -v150, v148, v96
	v_cmp_lt_f32_e64 s[12:13], 0, v148
	s_nop 1
	v_cndmask_b32_e64 v148, v149, v150, s[12:13]
	v_mul_f32_e32 v149, 0x37800000, v148
	v_cndmask_b32_e32 v148, v148, v149, vcc
	v_cmp_class_f32_e32 vcc, v96, v183
	s_nop 1
	v_cndmask_b32_e32 v96, v148, v96, vcc
	v_div_scale_f32 v148, s[10:11], v96, v96, 1.0
	v_rcp_f32_e32 v149, v148
	s_nop 0
	v_fma_f32 v150, -v148, v149, 1.0
	v_fmac_f32_e32 v149, v150, v149
	v_div_scale_f32 v150, vcc, 1.0, v96, 1.0
	v_mul_f32_e32 v151, v150, v149
	v_fma_f32 v152, -v148, v151, v150
	v_fmac_f32_e32 v151, v152, v149
	v_fma_f32 v148, -v148, v151, v150
	v_div_fmas_f32 v148, v148, v149, v151
	v_div_fixup_f32 v96, v148, v96, 1.0
	v_pk_mul_f32 v[148:149], v[104:105], v[96:97] op_sel_hi:[1,0]
	v_pk_mul_f32 v[150:151], v[106:107], v[96:97] op_sel_hi:[1,0]
	s_waitcnt vmcnt(2)
	v_pk_mul_f32 v[152:153], v[144:145], v[148:149]
	v_pk_mul_f32 v[154:155], v[146:147], v[150:151]
	v_pk_mul_f32 v[148:149], v[92:93], v[96:97] op_sel_hi:[1,0]
	v_pk_mul_f32 v[150:151], v[94:95], v[96:97] op_sel_hi:[1,0]
	v_pk_mul_f32 v[156:157], v[80:81], v[96:97] op_sel_hi:[1,0]
	v_pk_mul_f32 v[158:159], v[82:83], v[96:97] op_sel_hi:[1,0]
	v_pk_mul_f32 v[162:163], v[72:73], v[96:97] op_sel_hi:[1,0]
	v_pk_mul_f32 v[160:161], v[74:75], v[96:97] op_sel_hi:[1,0]
	v_pk_mul_f32 v[150:151], v[142:143], v[150:151]
	v_pk_mul_f32 v[148:149], v[140:141], v[148:149]
	v_pk_mul_f32 v[158:159], v[138:139], v[158:159]
	v_pk_mul_f32 v[156:157], v[136:137], v[156:157]
	v_pk_mul_f32 v[160:161], v[134:135], v[160:161]
	s_and_b64 vcc, exec, s[6:7]
	v_pk_mul_f32 v[192:193], v[132:133], v[162:163]
	s_cbranch_vccnz .LBB0_614
	v_pk_mul_f32 v[210:211], v[156:157], v[230:231]
	v_pk_mul_f32 v[162:163], v[158:159], v[232:233]
	v_pk_fma_f32 v[234:235], v[152:153], v[206:207], v[210:211] neg_lo:[0,0,1] neg_hi:[0,0,1]
	v_pk_mul_f32 v[152:153], v[152:153], v[230:231]
	v_pk_fma_f32 v[236:237], v[154:155], v[208:209], v[162:163] neg_lo:[0,0,1] neg_hi:[0,0,1]
	v_pk_mul_f32 v[154:155], v[154:155], v[232:233]
	v_pk_fma_f32 v[156:157], v[156:157], v[206:207], v[152:153]
	v_pk_mul_f32 v[152:153], v[160:161], v[228:229]
	v_pk_mul_f32 v[162:163], v[192:193], v[226:227]
	v_pk_fma_f32 v[158:159], v[158:159], v[208:209], v[154:155]
	v_pk_fma_f32 v[154:155], v[150:151], v[204:205], v[152:153] neg_lo:[0,0,1] neg_hi:[0,0,1]
	v_pk_fma_f32 v[152:153], v[148:149], v[202:203], v[162:163] neg_lo:[0,0,1] neg_hi:[0,0,1]
	v_pk_mul_f32 v[150:151], v[150:151], v[228:229]
	v_pk_mul_f32 v[148:149], v[148:149], v[226:227]
	v_pk_fma_f32 v[160:161], v[160:161], v[204:205], v[150:151]
	v_pk_fma_f32 v[192:193], v[192:193], v[202:203], v[148:149]
	v_mov_b64_e32 v[148:149], v[152:153]
	v_mov_b64_e32 v[150:151], v[154:155]
	v_mov_b64_e32 v[152:153], v[234:235]
	v_mov_b64_e32 v[154:155], v[236:237]

; DI u32x4 pk8(const f32x4& a, const f32x4& b) { u32x4 w; w.x = pk2(a[0], a[1]); w.y = pk2(a[2], a[3]); w.z = pk2(b[0], b[1]); w.w = pk2(b[2], b[3]); return w; }
; DI float shx(float v, int m, int lane) { return __int_as_float(__builtin_amdgcn_ds_bpermute((lane ^ m) << 2, __float_as_int(v))); }
; #define FOR_AI_M _Pragma("unroll") for (int ai = 0; ai < 2; ++ai) _Pragma("unroll") for (int m = 0; m < 4; ++m)
;     DI void operator()(Acc& acc, const Unit& u, int wr, int wc, int fr, int fq) const {
;     ...
;         FOR_AI_M { const int r = row0 + EPI_ROWS(ai, m);
;             f32x4 x[2][2];
; #pragma unroll
;             for (int bj = 0; bj < 2; ++bj) { x[bj][0] = acc[ai][bj][m][0]; x[bj][1] = acc[ai][bj][m][1]; }
;             if (!is_v) {
;                 float s = 0.f;
; #pragma unroll
;                 for (int bj = 0; bj < 2; ++bj)
; #pragma unroll
;                     for (int n = 0; n < 2; ++n) s += (x[bj][n][0] * x[bj][n][0] + x[bj][n][1] * x[bj][n][1]) + (x[bj][n][2] * x[bj][n][2] + x[bj][n][3] * x[bj][n][3]);
;                 s += shx(s, 16, fr + 16 * fq); s += shx(s, 32, fr + 16 * fq);
;                 const float rstd = 1.f / sqrtf(s * (1.f / 64.f) + EPS);
; #pragma unroll
;                 for (int bj = 0; bj < 2; ++bj)
; #pragma unroll
;                     for (int n = 0; n < 2; ++n) x[bj][n] = x[bj][n] * rstd * gv[bj][n];
;                 if (rope) {
;                     const float* rr = rg + (size_t)(r & 2047) * 64 + 8 * fq;
; #pragma unroll
;                     for (int n = 0; n < 2; ++n) { const f32x4 cs = *(const f32x4*)(rr + 4 * n), sn = *(const f32x4*)(rr + 32 + 4 * n);
;                         const f32x4 x1 = x[0][n], x2 = x[1][n]; x[0][n] = x1 * cs - x2 * sn; x[1][n] = x1 * sn + x2 * cs; }
;                 }
; #pragma unroll
;                 for (int bj = 0; bj < 2; ++bj)
; #pragma unroll
;                     for (int n = 0; n < 2; ++n) x[bj][n] = x[bj][n] * qs;
;             }
; #pragma unroll
;             for (int bj = 0; bj < 2; ++bj) *(u32x4*)(dst + (size_t)r * ld + colb + 32 * bj + 8 * fq) = pk8(x[bj][0], x[bj][1]);
.LBB0_615:
	v_mad_i64_i32 v[192:193], s[10:11], s42, v200, 0
	v_lshl_add_u64 v[192:193], v[192:193], 1, v[98:99]
	v_cvt_pk_bf16_f32 v152, v152, v153
	v_cvt_pk_bf16_f32 v153, v154, v155
	v_cvt_pk_bf16_f32 v154, v148, v149
	v_cvt_pk_bf16_f32 v155, v150, v151
	v_cvt_pk_bf16_f32 v148, v156, v157
	v_cvt_pk_bf16_f32 v149, v158, v159
	v_cvt_pk_bf16_f32 v150, v160, v161
	v_cvt_pk_bf16_f32 v151, v162, v163
	v_add_u32_e32 v248, 0x3000, v251
	v_lshl_add_u64 v[252:253], v[176:177], 0, v[248:249]
	global_load_dwordx4 v[202:205], v[252:253], off offset:16
	global_load_dwordx4 v[206:209], v[252:253], off
	global_load_dwordx4 v[226:229], v[252:253], off offset:144
	global_load_dwordx4 v[230:233], v[252:253], off offset:128
	global_store_dwordx4 v[192:193], v[152:155], off
	global_store_dwordx4 v[192:193], v[148:151], off offset:64
	v_mov_b64_e32 v[158:159], v[70:71]
	v_mov_b64_e32 v[154:155], v[86:87]
	v_mov_b64_e32 v[150:151], v[78:79]
	v_mov_b64_e32 v[162:163], v[66:67]
	v_or_b32_e32 v200, 48, v199
	s_and_b64 vcc, exec, s[8:9]
	v_mov_b64_e32 v[152:153], v[84:85]
	v_mov_b64_e32 v[148:149], v[76:77]
	v_mov_b64_e32 v[156:157], v[68:69]
	v_mov_b64_e32 v[160:161], v[64:65]
	s_cbranch_vccnz .LBB0_619
	v_pk_mul_f32 v[148:149], v[86:87], v[86:87]
	v_pk_mul_f32 v[150:151], v[84:85], v[84:85]
	v_mul_f32_e32 v96, v68, v68
	v_pk_mov_b32 v[152:153], v[150:151], v[148:149] op_sel:[1,0]
	v_mov_b32_e32 v151, v149
	v_pk_add_f32 v[148:149], v[152:153], v[150:151]
	v_pk_mul_f32 v[150:151], v[78:79], v[78:79]
	v_pk_mul_f32 v[152:153], v[76:77], v[76:77]
	v_pk_add_f32 v[148:149], v[148:149], v[148:149] op_sel_hi:[0,1]
	v_pk_mov_b32 v[154:155], v[152:153], v[150:151] op_sel:[1,0]
	v_mov_b32_e32 v153, v151
	v_pk_add_f32 v[150:151], v[154:155], v[152:153]
	v_pk_fma_f32 v[152:153], v[68:69], v[68:69], v[96:97] op_sel_hi:[1,1,0]
	v_mul_f32_e32 v96, v70, v70
	v_pk_add_f32 v[150:151], v[150:151], v[150:151] op_sel_hi:[0,1]
	v_pk_fma_f32 v[154:155], v[70:71], v[70:71], v[96:97] op_sel_hi:[1,1,0]
	v_mul_f32_e32 v152, v64, v64
	v_mul_f32_e32 v154, v65, v65
	v_mul_f32_e32 v150, v66, v66
	v_mul_f32_e32 v148, v67, v67
	v_pk_add_f32 v[152:153], v[152:153], v[154:155]
	v_pk_add_f32 v[148:149], v[150:151], v[148:149]
	s_nop 0
	v_pk_add_f32 v[148:149], v[152:153], v[148:149]
	s_nop 0
	v_add_f32_e32 v96, v148, v149
	ds_bpermute_b32 v148, v194, v96
	s_waitcnt lgkmcnt(0)
	v_add_f32_e32 v96, v96, v148
	ds_bpermute_b32 v148, v195, v96
	s_waitcnt lgkmcnt(0)
	v_add_f32_e32 v96, v96, v148
	v_fmamk_f32 v96, v96, 0x3c800000, v185
	v_mul_f32_e32 v148, 0x4f800000, v96
	v_cmp_gt_f32_e32 vcc, s65, v96
	s_nop 1
	v_cndmask_b32_e32 v96, v96, v148, vcc
	v_sqrt_f32_e32 v148, v96
	s_nop 0
	v_add_u32_e32 v149, -1, v148
	v_fma_f32 v150, -v149, v148, v96
	v_cmp_ge_f32_e64 s[12:13], 0, v150
	v_add_u32_e32 v150, 1, v148
	s_nop 0
	v_cndmask_b32_e64 v149, v148, v149, s[12:13]
	v_fma_f32 v148, -v150, v148, v96
	v_cmp_lt_f32_e64 s[12:13], 0, v148
	s_nop 1
	v_cndmask_b32_e64 v148, v149, v150, s[12:13]
	v_mul_f32_e32 v149, 0x37800000, v148
	v_cndmask_b32_e32 v148, v148, v149, vcc
	v_cmp_class_f32_e32 vcc, v96, v183
	s_nop 1
	v_cndmask_b32_e32 v96, v148, v96, vcc
	v_div_scale_f32 v148, s[10:11], v96, v96, 1.0
	v_rcp_f32_e32 v149, v148
	s_nop 0
	v_fma_f32 v150, -v148, v149, 1.0
	v_fmac_f32_e32 v149, v150, v149
	v_div_scale_f32 v150, vcc, 1.0, v96, 1.0
	v_mul_f32_e32 v151, v150, v149
	v_fma_f32 v152, -v148, v151, v150
	v_fmac_f32_e32 v151, v152, v149
	v_fma_f32 v148, -v148, v151, v150
	v_div_fmas_f32 v148, v148, v149, v151
	v_div_fixup_f32 v96, v148, v96, 1.0
	v_pk_mul_f32 v[148:149], v[84:85], v[96:97] op_sel_hi:[1,0]
	v_pk_mul_f32 v[150:151], v[86:87], v[96:97] op_sel_hi:[1,0]
	s_waitcnt vmcnt(2)
	v_pk_mul_f32 v[152:153], v[144:145], v[148:149]
	v_pk_mul_f32 v[154:155], v[146:147], v[150:151]
	v_pk_mul_f32 v[148:149], v[76:77], v[96:97] op_sel_hi:[1,0]
	v_pk_mul_f32 v[150:151], v[78:79], v[96:97] op_sel_hi:[1,0]
	v_pk_mul_f32 v[156:157], v[68:69], v[96:97] op_sel_hi:[1,0]
	v_pk_mul_f32 v[158:159], v[70:71], v[96:97] op_sel_hi:[1,0]
	v_pk_mul_f32 v[162:163], v[64:65], v[96:97] op_sel_hi:[1,0]
	v_pk_mul_f32 v[160:161], v[66:67], v[96:97] op_sel_hi:[1,0]
	v_pk_mul_f32 v[150:151], v[142:143], v[150:151]
	v_pk_mul_f32 v[148:149], v[140:141], v[148:149]
	v_pk_mul_f32 v[158:159], v[138:139], v[158:159]
	v_pk_mul_f32 v[156:157], v[136:137], v[156:157]
	v_pk_mul_f32 v[160:161], v[134:135], v[160:161]
	s_and_b64 vcc, exec, s[6:7]
	v_pk_mul_f32 v[192:193], v[132:133], v[162:163]
	s_cbranch_vccnz .LBB0_618
	v_pk_mul_f32 v[210:211], v[156:157], v[230:231]
	v_pk_mul_f32 v[162:163], v[158:159], v[232:233]
	v_pk_fma_f32 v[234:235], v[152:153], v[206:207], v[210:211] neg_lo:[0,0,1] neg_hi:[0,0,1]
	v_pk_mul_f32 v[152:153], v[152:153], v[230:231]
	v_pk_fma_f32 v[236:237], v[154:155], v[208:209], v[162:163] neg_lo:[0,0,1] neg_hi:[0,0,1]
	v_pk_mul_f32 v[154:155], v[154:155], v[232:233]
	v_pk_fma_f32 v[156:157], v[156:157], v[206:207], v[152:153]
	v_pk_mul_f32 v[152:153], v[160:161], v[228:229]
	v_pk_mul_f32 v[162:163], v[192:193], v[226:227]
	v_pk_fma_f32 v[158:159], v[158:159], v[208:209], v[154:155]
	v_pk_fma_f32 v[154:155], v[150:151], v[204:205], v[152:153] neg_lo:[0,0,1] neg_hi:[0,0,1]
	v_pk_fma_f32 v[152:153], v[148:149], v[202:203], v[162:163] neg_lo:[0,0,1] neg_hi:[0,0,1]
	v_pk_mul_f32 v[150:151], v[150:151], v[228:229]
	v_pk_mul_f32 v[148:149], v[148:149], v[226:227]
	v_pk_fma_f32 v[160:161], v[160:161], v[204:205], v[150:151]
	v_pk_fma_f32 v[192:193], v[192:193], v[202:203], v[148:149]
	v_mov_b64_e32 v[148:149], v[152:153]
	v_mov_b64_e32 v[150:151], v[154:155]
	v_mov_b64_e32 v[152:153], v[234:235]
	v_mov_b64_e32 v[154:155], v[236:237]

; DI u32x4 pk8(const f32x4& a, const f32x4& b) { u32x4 w; w.x = pk2(a[0], a[1]); w.y = pk2(a[2], a[3]); w.z = pk2(b[0], b[1]); w.w = pk2(b[2], b[3]); return w; }
; DI float shx(float v, int m, int lane) { return __int_as_float(__builtin_amdgcn_ds_bpermute((lane ^ m) << 2, __float_as_int(v))); }
; #define FOR_AI_M _Pragma("unroll") for (int ai = 0; ai < 2; ++ai) _Pragma("unroll") for (int m = 0; m < 4; ++m)
;     DI void operator()(Acc& acc, const Unit& u, int wr, int wc, int fr, int fq) const {
;     ...
;         FOR_AI_M { const int r = row0 + EPI_ROWS(ai, m);
;             f32x4 x[2][2];
; #pragma unroll
;             for (int bj = 0; bj < 2; ++bj) { x[bj][0] = acc[ai][bj][m][0]; x[bj][1] = acc[ai][bj][m][1]; }
;             if (!is_v) {
;                 float s = 0.f;
; #pragma unroll
;                 for (int bj = 0; bj < 2; ++bj)
; #pragma unroll
;                     for (int n = 0; n < 2; ++n) s += (x[bj][n][0] * x[bj][n][0] + x[bj][n][1] * x[bj][n][1]) + (x[bj][n][2] * x[bj][n][2] + x[bj][n][3] * x[bj][n][3]);
;                 s += shx(s, 16, fr + 16 * fq); s += shx(s, 32, fr + 16 * fq);
;                 const float rstd = 1.f / sqrtf(s * (1.f / 64.f) + EPS);
; #pragma unroll
;                 for (int bj = 0; bj < 2; ++bj)
; #pragma unroll
;                     for (int n = 0; n < 2; ++n) x[bj][n] = x[bj][n] * rstd * gv[bj][n];
;                 if (rope) {
;                     const float* rr = rg + (size_t)(r & 2047) * 64 + 8 * fq;
; #pragma unroll
;                     for (int n = 0; n < 2; ++n) { const f32x4 cs = *(const f32x4*)(rr + 4 * n), sn = *(const f32x4*)(rr + 32 + 4 * n);
;                         const f32x4 x1 = x[0][n], x2 = x[1][n]; x[0][n] = x1 * cs - x2 * sn; x[1][n] = x1 * sn + x2 * cs; }
;                 }
; #pragma unroll
;                 for (int bj = 0; bj < 2; ++bj)
; #pragma unroll
;                     for (int n = 0; n < 2; ++n) x[bj][n] = x[bj][n] * qs;
;             }
; #pragma unroll
;             for (int bj = 0; bj < 2; ++bj) *(u32x4*)(dst + (size_t)r * ld + colb + 32 * bj + 8 * fq) = pk8(x[bj][0], x[bj][1]);
.LBB0_619:
	v_mad_i64_i32 v[192:193], s[10:11], s42, v200, 0
	v_lshl_add_u64 v[192:193], v[192:193], 1, v[98:99]
	v_cvt_pk_bf16_f32 v152, v152, v153
	v_cvt_pk_bf16_f32 v153, v154, v155
	v_cvt_pk_bf16_f32 v154, v148, v149
	v_cvt_pk_bf16_f32 v155, v150, v151
	v_cvt_pk_bf16_f32 v148, v156, v157
	v_cvt_pk_bf16_f32 v149, v158, v159
	v_cvt_pk_bf16_f32 v150, v160, v161
	v_cvt_pk_bf16_f32 v151, v162, v163
	v_add_u32_e32 v248, 0x8000, v251
	v_lshl_add_u64 v[252:253], v[176:177], 0, v[248:249]
	global_load_dwordx4 v[202:205], v[252:253], off offset:16
	global_load_dwordx4 v[206:209], v[252:253], off
	global_load_dwordx4 v[226:229], v[252:253], off offset:144
	global_load_dwordx4 v[230:233], v[252:253], off offset:128
	global_store_dwordx4 v[192:193], v[152:155], off
	global_store_dwordx4 v[192:193], v[148:151], off offset:64
	v_mov_b64_e32 v[158:159], v[50:51]
	v_mov_b64_e32 v[154:155], v[62:63]
	v_mov_b64_e32 v[150:151], v[58:59]
	v_mov_b64_e32 v[162:163], v[42:43]
	v_add_u32_e32 v200, 0x80, v199
	s_and_b64 vcc, exec, s[8:9]
	v_mov_b64_e32 v[152:153], v[60:61]
	v_mov_b64_e32 v[148:149], v[56:57]
	v_mov_b64_e32 v[156:157], v[48:49]
	v_mov_b64_e32 v[160:161], v[40:41]
	s_cbranch_vccnz .LBB0_623
	v_pk_mul_f32 v[148:149], v[62:63], v[62:63]
	v_pk_mul_f32 v[150:151], v[60:61], v[60:61]
	v_mul_f32_e32 v96, v48, v48
	v_pk_mov_b32 v[152:153], v[150:151], v[148:149] op_sel:[1,0]
	v_mov_b32_e32 v151, v149
	v_pk_add_f32 v[148:149], v[152:153], v[150:151]
	v_pk_mul_f32 v[150:151], v[58:59], v[58:59]
	v_pk_mul_f32 v[152:153], v[56:57], v[56:57]
	v_pk_add_f32 v[148:149], v[148:149], v[148:149] op_sel_hi:[0,1]
	v_pk_mov_b32 v[154:155], v[152:153], v[150:151] op_sel:[1,0]
	v_mov_b32_e32 v153, v151
	v_pk_add_f32 v[150:151], v[154:155], v[152:153]
	v_pk_fma_f32 v[152:153], v[48:49], v[48:49], v[96:97] op_sel_hi:[1,1,0]
	v_mul_f32_e32 v96, v50, v50
	v_pk_add_f32 v[150:151], v[150:151], v[150:151] op_sel_hi:[0,1]
	v_pk_fma_f32 v[154:155], v[50:51], v[50:51], v[96:97] op_sel_hi:[1,1,0]
	v_mul_f32_e32 v152, v40, v40
	v_mul_f32_e32 v154, v41, v41
	v_mul_f32_e32 v150, v42, v42
	v_mul_f32_e32 v148, v43, v43
	v_pk_add_f32 v[152:153], v[152:153], v[154:155]
	v_pk_add_f32 v[148:149], v[150:151], v[148:149]
	s_nop 0
	v_pk_add_f32 v[148:149], v[152:153], v[148:149]
	s_nop 0
	v_add_f32_e32 v96, v148, v149
	ds_bpermute_b32 v148, v194, v96
	s_waitcnt lgkmcnt(0)
	v_add_f32_e32 v96, v96, v148
	ds_bpermute_b32 v148, v195, v96
	s_waitcnt lgkmcnt(0)
	v_add_f32_e32 v96, v96, v148
	v_fmamk_f32 v96, v96, 0x3c800000, v185
	v_mul_f32_e32 v148, 0x4f800000, v96
	v_cmp_gt_f32_e32 vcc, s65, v96
	s_nop 1
	v_cndmask_b32_e32 v96, v96, v148, vcc
	v_sqrt_f32_e32 v148, v96
	s_nop 0
	v_add_u32_e32 v149, -1, v148
	v_fma_f32 v150, -v149, v148, v96
	v_cmp_ge_f32_e64 s[12:13], 0, v150
	v_add_u32_e32 v150, 1, v148
	s_nop 0
	v_cndmask_b32_e64 v149, v148, v149, s[12:13]
	v_fma_f32 v148, -v150, v148, v96
	v_cmp_lt_f32_e64 s[12:13], 0, v148
	s_nop 1
	v_cndmask_b32_e64 v148, v149, v150, s[12:13]
	v_mul_f32_e32 v149, 0x37800000, v148
	v_cndmask_b32_e32 v148, v148, v149, vcc
	v_cmp_class_f32_e32 vcc, v96, v183
	s_nop 1
	v_cndmask_b32_e32 v96, v148, v96, vcc
	v_div_scale_f32 v148, s[10:11], v96, v96, 1.0
	v_rcp_f32_e32 v149, v148
	s_nop 0
	v_fma_f32 v150, -v148, v149, 1.0
	v_fmac_f32_e32 v149, v150, v149
	v_div_scale_f32 v150, vcc, 1.0, v96, 1.0
	v_mul_f32_e32 v151, v150, v149
	v_fma_f32 v152, -v148, v151, v150
	v_fmac_f32_e32 v151, v152, v149
	v_fma_f32 v148, -v148, v151, v150
	v_div_fmas_f32 v148, v148, v149, v151
	v_div_fixup_f32 v96, v148, v96, 1.0
	v_pk_mul_f32 v[148:149], v[60:61], v[96:97] op_sel_hi:[1,0]
	v_pk_mul_f32 v[150:151], v[62:63], v[96:97] op_sel_hi:[1,0]
	s_waitcnt vmcnt(2)
	v_pk_mul_f32 v[152:153], v[144:145], v[148:149]
	v_pk_mul_f32 v[154:155], v[146:147], v[150:151]
	v_pk_mul_f32 v[148:149], v[56:57], v[96:97] op_sel_hi:[1,0]
	v_pk_mul_f32 v[150:151], v[58:59], v[96:97] op_sel_hi:[1,0]
	v_pk_mul_f32 v[156:157], v[48:49], v[96:97] op_sel_hi:[1,0]
	v_pk_mul_f32 v[158:159], v[50:51], v[96:97] op_sel_hi:[1,0]
	v_pk_mul_f32 v[162:163], v[40:41], v[96:97] op_sel_hi:[1,0]
	v_pk_mul_f32 v[160:161], v[42:43], v[96:97] op_sel_hi:[1,0]
	v_pk_mul_f32 v[150:151], v[142:143], v[150:151]
	v_pk_mul_f32 v[148:149], v[140:141], v[148:149]
	v_pk_mul_f32 v[158:159], v[138:139], v[158:159]
	v_pk_mul_f32 v[156:157], v[136:137], v[156:157]
	v_pk_mul_f32 v[160:161], v[134:135], v[160:161]
	s_and_b64 vcc, exec, s[6:7]
	v_pk_mul_f32 v[192:193], v[132:133], v[162:163]
	s_cbranch_vccnz .LBB0_622
	v_pk_mul_f32 v[210:211], v[156:157], v[230:231]
	v_pk_mul_f32 v[162:163], v[158:159], v[232:233]
	v_pk_fma_f32 v[234:235], v[152:153], v[206:207], v[210:211] neg_lo:[0,0,1] neg_hi:[0,0,1]
	v_pk_mul_f32 v[152:153], v[152:153], v[230:231]
	v_pk_fma_f32 v[236:237], v[154:155], v[208:209], v[162:163] neg_lo:[0,0,1] neg_hi:[0,0,1]
	v_pk_mul_f32 v[154:155], v[154:155], v[232:233]
	v_pk_fma_f32 v[156:157], v[156:157], v[206:207], v[152:153]
	v_pk_mul_f32 v[152:153], v[160:161], v[228:229]
	v_pk_mul_f32 v[162:163], v[192:193], v[226:227]
	v_pk_fma_f32 v[158:159], v[158:159], v[208:209], v[154:155]
	v_pk_fma_f32 v[154:155], v[150:151], v[204:205], v[152:153] neg_lo:[0,0,1] neg_hi:[0,0,1]
	v_pk_fma_f32 v[152:153], v[148:149], v[202:203], v[162:163] neg_lo:[0,0,1] neg_hi:[0,0,1]
	v_pk_mul_f32 v[150:151], v[150:151], v[228:229]
	v_pk_mul_f32 v[148:149], v[148:149], v[226:227]
	v_pk_fma_f32 v[160:161], v[160:161], v[204:205], v[150:151]
	v_pk_fma_f32 v[192:193], v[192:193], v[202:203], v[148:149]
	v_mov_b64_e32 v[148:149], v[152:153]
	v_mov_b64_e32 v[150:151], v[154:155]
	v_mov_b64_e32 v[152:153], v[234:235]
	v_mov_b64_e32 v[154:155], v[236:237]

; DI u32x4 pk8(const f32x4& a, const f32x4& b) { u32x4 w; w.x = pk2(a[0], a[1]); w.y = pk2(a[2], a[3]); w.z = pk2(b[0], b[1]); w.w = pk2(b[2], b[3]); return w; }
; DI float shx(float v, int m, int lane) { return __int_as_float(__builtin_amdgcn_ds_bpermute((lane ^ m) << 2, __float_as_int(v))); }
; #define FOR_AI_M _Pragma("unroll") for (int ai = 0; ai < 2; ++ai) _Pragma("unroll") for (int m = 0; m < 4; ++m)
;     DI void operator()(Acc& acc, const Unit& u, int wr, int wc, int fr, int fq) const {
;     ...
;         FOR_AI_M { const int r = row0 + EPI_ROWS(ai, m);
;             f32x4 x[2][2];
; #pragma unroll
;             for (int bj = 0; bj < 2; ++bj) { x[bj][0] = acc[ai][bj][m][0]; x[bj][1] = acc[ai][bj][m][1]; }
;             if (!is_v) {
;                 float s = 0.f;
; #pragma unroll
;                 for (int bj = 0; bj < 2; ++bj)
; #pragma unroll
;                     for (int n = 0; n < 2; ++n) s += (x[bj][n][0] * x[bj][n][0] + x[bj][n][1] * x[bj][n][1]) + (x[bj][n][2] * x[bj][n][2] + x[bj][n][3] * x[bj][n][3]);
;                 s += shx(s, 16, fr + 16 * fq); s += shx(s, 32, fr + 16 * fq);
;                 const float rstd = 1.f / sqrtf(s * (1.f / 64.f) + EPS);
; #pragma unroll
;                 for (int bj = 0; bj < 2; ++bj)
; #pragma unroll
;                     for (int n = 0; n < 2; ++n) x[bj][n] = x[bj][n] * rstd * gv[bj][n];
;                 if (rope) {
;                     const float* rr = rg + (size_t)(r & 2047) * 64 + 8 * fq;
; #pragma unroll
;                     for (int n = 0; n < 2; ++n) { const f32x4 cs = *(const f32x4*)(rr + 4 * n), sn = *(const f32x4*)(rr + 32 + 4 * n);
;                         const f32x4 x1 = x[0][n], x2 = x[1][n]; x[0][n] = x1 * cs - x2 * sn; x[1][n] = x1 * sn + x2 * cs; }
;                 }
; #pragma unroll
;                 for (int bj = 0; bj < 2; ++bj)
; #pragma unroll
;                     for (int n = 0; n < 2; ++n) x[bj][n] = x[bj][n] * qs;
;             }
; #pragma unroll
;             for (int bj = 0; bj < 2; ++bj) *(u32x4*)(dst + (size_t)r * ld + colb + 32 * bj + 8 * fq) = pk8(x[bj][0], x[bj][1]);
.LBB0_623:
	v_mad_i64_i32 v[192:193], s[10:11], s42, v200, 0
	v_lshl_add_u64 v[192:193], v[192:193], 1, v[98:99]
	v_cvt_pk_bf16_f32 v152, v152, v153
	v_cvt_pk_bf16_f32 v153, v154, v155
	v_cvt_pk_bf16_f32 v154, v148, v149
	v_cvt_pk_bf16_f32 v155, v150, v151
	v_cvt_pk_bf16_f32 v148, v156, v157
	v_cvt_pk_bf16_f32 v149, v158, v159
	v_cvt_pk_bf16_f32 v150, v160, v161
	v_cvt_pk_bf16_f32 v151, v162, v163
	v_add_u32_e32 v248, 0x9000, v251
	v_lshl_add_u64 v[252:253], v[176:177], 0, v[248:249]
	global_load_dwordx4 v[202:205], v[252:253], off offset:16
	global_load_dwordx4 v[206:209], v[252:253], off
	global_load_dwordx4 v[226:229], v[252:253], off offset:144
	global_load_dwordx4 v[230:233], v[252:253], off offset:128
	global_store_dwordx4 v[192:193], v[152:155], off
	global_store_dwordx4 v[192:193], v[148:151], off offset:64
	v_mov_b64_e32 v[158:159], v[34:35]
	v_mov_b64_e32 v[154:155], v[54:55]
	v_mov_b64_e32 v[150:151], v[46:47]
	v_mov_b64_e32 v[162:163], v[26:27]
	v_add_u32_e32 v200, 0x90, v199
	s_and_b64 vcc, exec, s[8:9]
	v_mov_b64_e32 v[152:153], v[52:53]
	v_mov_b64_e32 v[148:149], v[44:45]
	v_mov_b64_e32 v[156:157], v[32:33]
	v_mov_b64_e32 v[160:161], v[24:25]
	s_cbranch_vccnz .LBB0_627
	v_pk_mul_f32 v[148:149], v[54:55], v[54:55]
	v_pk_mul_f32 v[150:151], v[52:53], v[52:53]
	v_mul_f32_e32 v96, v32, v32
	v_pk_mov_b32 v[152:153], v[150:151], v[148:149] op_sel:[1,0]
	v_mov_b32_e32 v151, v149
	v_pk_add_f32 v[148:149], v[152:153], v[150:151]
	v_pk_mul_f32 v[150:151], v[46:47], v[46:47]
	v_pk_mul_f32 v[152:153], v[44:45], v[44:45]
	v_pk_add_f32 v[148:149], v[148:149], v[148:149] op_sel_hi:[0,1]
	v_pk_mov_b32 v[154:155], v[152:153], v[150:151] op_sel:[1,0]
	v_mov_b32_e32 v153, v151
	v_pk_add_f32 v[150:151], v[154:155], v[152:153]
	v_pk_fma_f32 v[152:153], v[32:33], v[32:33], v[96:97] op_sel_hi:[1,1,0]
	v_mul_f32_e32 v96, v34, v34
	v_pk_add_f32 v[150:151], v[150:151], v[150:151] op_sel_hi:[0,1]
	v_pk_fma_f32 v[154:155], v[34:35], v[34:35], v[96:97] op_sel_hi:[1,1,0]
	v_mul_f32_e32 v152, v24, v24
	v_mul_f32_e32 v154, v25, v25
	v_mul_f32_e32 v150, v26, v26
	v_mul_f32_e32 v148, v27, v27
	v_pk_add_f32 v[152:153], v[152:153], v[154:155]
	v_pk_add_f32 v[148:149], v[150:151], v[148:149]
	s_nop 0
	v_pk_add_f32 v[148:149], v[152:153], v[148:149]
	s_nop 0
	v_add_f32_e32 v96, v148, v149
	ds_bpermute_b32 v148, v194, v96
	s_waitcnt lgkmcnt(0)
	v_add_f32_e32 v96, v96, v148
	ds_bpermute_b32 v148, v195, v96
	s_waitcnt lgkmcnt(0)
	v_add_f32_e32 v96, v96, v148
	v_fmamk_f32 v96, v96, 0x3c800000, v185
	v_mul_f32_e32 v148, 0x4f800000, v96
	v_cmp_gt_f32_e32 vcc, s65, v96
	s_nop 1
	v_cndmask_b32_e32 v96, v96, v148, vcc
	v_sqrt_f32_e32 v148, v96
	s_nop 0
	v_add_u32_e32 v149, -1, v148
	v_fma_f32 v150, -v149, v148, v96
	v_cmp_ge_f32_e64 s[12:13], 0, v150
	v_add_u32_e32 v150, 1, v148
	s_nop 0
	v_cndmask_b32_e64 v149, v148, v149, s[12:13]
	v_fma_f32 v148, -v150, v148, v96
	v_cmp_lt_f32_e64 s[12:13], 0, v148
	s_nop 1
	v_cndmask_b32_e64 v148, v149, v150, s[12:13]
	v_mul_f32_e32 v149, 0x37800000, v148
	v_cndmask_b32_e32 v148, v148, v149, vcc
	v_cmp_class_f32_e32 vcc, v96, v183
	s_nop 1
	v_cndmask_b32_e32 v96, v148, v96, vcc
	v_div_scale_f32 v148, s[10:11], v96, v96, 1.0
	v_rcp_f32_e32 v149, v148
	s_nop 0
	v_fma_f32 v150, -v148, v149, 1.0
	v_fmac_f32_e32 v149, v150, v149
	v_div_scale_f32 v150, vcc, 1.0, v96, 1.0
	v_mul_f32_e32 v151, v150, v149
	v_fma_f32 v152, -v148, v151, v150
	v_fmac_f32_e32 v151, v152, v149
	v_fma_f32 v148, -v148, v151, v150
	v_div_fmas_f32 v148, v148, v149, v151
	v_div_fixup_f32 v96, v148, v96, 1.0
	v_pk_mul_f32 v[148:149], v[52:53], v[96:97] op_sel_hi:[1,0]
	v_pk_mul_f32 v[150:151], v[54:55], v[96:97] op_sel_hi:[1,0]
	s_waitcnt vmcnt(2)
	v_pk_mul_f32 v[152:153], v[144:145], v[148:149]
	v_pk_mul_f32 v[154:155], v[146:147], v[150:151]
	v_pk_mul_f32 v[148:149], v[44:45], v[96:97] op_sel_hi:[1,0]
	v_pk_mul_f32 v[150:151], v[46:47], v[96:97] op_sel_hi:[1,0]
	v_pk_mul_f32 v[156:157], v[32:33], v[96:97] op_sel_hi:[1,0]
	v_pk_mul_f32 v[158:159], v[34:35], v[96:97] op_sel_hi:[1,0]
	v_pk_mul_f32 v[162:163], v[24:25], v[96:97] op_sel_hi:[1,0]
	v_pk_mul_f32 v[160:161], v[26:27], v[96:97] op_sel_hi:[1,0]
	v_pk_mul_f32 v[150:151], v[142:143], v[150:151]
	v_pk_mul_f32 v[148:149], v[140:141], v[148:149]
	v_pk_mul_f32 v[158:159], v[138:139], v[158:159]
	v_pk_mul_f32 v[156:157], v[136:137], v[156:157]
	v_pk_mul_f32 v[160:161], v[134:135], v[160:161]
	s_and_b64 vcc, exec, s[6:7]
	v_pk_mul_f32 v[192:193], v[132:133], v[162:163]
	s_cbranch_vccnz .LBB0_626
	v_pk_mul_f32 v[210:211], v[156:157], v[230:231]
	v_pk_mul_f32 v[162:163], v[158:159], v[232:233]
	v_pk_fma_f32 v[234:235], v[152:153], v[206:207], v[210:211] neg_lo:[0,0,1] neg_hi:[0,0,1]
	v_pk_mul_f32 v[152:153], v[152:153], v[230:231]
	v_pk_fma_f32 v[236:237], v[154:155], v[208:209], v[162:163] neg_lo:[0,0,1] neg_hi:[0,0,1]
	v_pk_mul_f32 v[154:155], v[154:155], v[232:233]
	v_pk_fma_f32 v[156:157], v[156:157], v[206:207], v[152:153]
	v_pk_mul_f32 v[152:153], v[160:161], v[228:229]
	v_pk_mul_f32 v[162:163], v[192:193], v[226:227]
	v_pk_fma_f32 v[158:159], v[158:159], v[208:209], v[154:155]
	v_pk_fma_f32 v[154:155], v[150:151], v[204:205], v[152:153] neg_lo:[0,0,1] neg_hi:[0,0,1]
	v_pk_fma_f32 v[152:153], v[148:149], v[202:203], v[162:163] neg_lo:[0,0,1] neg_hi:[0,0,1]
	v_pk_mul_f32 v[150:151], v[150:151], v[228:229]
	v_pk_mul_f32 v[148:149], v[148:149], v[226:227]
	v_pk_fma_f32 v[160:161], v[160:161], v[204:205], v[150:151]
	v_pk_fma_f32 v[192:193], v[192:193], v[202:203], v[148:149]
	v_mov_b64_e32 v[148:149], v[152:153]
	v_mov_b64_e32 v[150:151], v[154:155]
	v_mov_b64_e32 v[152:153], v[234:235]
	v_mov_b64_e32 v[154:155], v[236:237]

; DI u32x4 pk8(const f32x4& a, const f32x4& b) { u32x4 w; w.x = pk2(a[0], a[1]); w.y = pk2(a[2], a[3]); w.z = pk2(b[0], b[1]); w.w = pk2(b[2], b[3]); return w; }
; DI float shx(float v, int m, int lane) { return __int_as_float(__builtin_amdgcn_ds_bpermute((lane ^ m) << 2, __float_as_int(v))); }
; #define FOR_AI_M _Pragma("unroll") for (int ai = 0; ai < 2; ++ai) _Pragma("unroll") for (int m = 0; m < 4; ++m)
;     DI void operator()(Acc& acc, const Unit& u, int wr, int wc, int fr, int fq) const {
;     ...
;         FOR_AI_M { const int r = row0 + EPI_ROWS(ai, m);
;             f32x4 x[2][2];
; #pragma unroll
;             for (int bj = 0; bj < 2; ++bj) { x[bj][0] = acc[ai][bj][m][0]; x[bj][1] = acc[ai][bj][m][1]; }
;             if (!is_v) {
;                 float s = 0.f;
; #pragma unroll
;                 for (int bj = 0; bj < 2; ++bj)
; #pragma unroll
;                     for (int n = 0; n < 2; ++n) s += (x[bj][n][0] * x[bj][n][0] + x[bj][n][1] * x[bj][n][1]) + (x[bj][n][2] * x[bj][n][2] + x[bj][n][3] * x[bj][n][3]);
;                 s += shx(s, 16, fr + 16 * fq); s += shx(s, 32, fr + 16 * fq);
;                 const float rstd = 1.f / sqrtf(s * (1.f / 64.f) + EPS);
; #pragma unroll
;                 for (int bj = 0; bj < 2; ++bj)
; #pragma unroll
;                     for (int n = 0; n < 2; ++n) x[bj][n] = x[bj][n] * rstd * gv[bj][n];
;                 if (rope) {
;                     const float* rr = rg + (size_t)(r & 2047) * 64 + 8 * fq;
; #pragma unroll
;                     for (int n = 0; n < 2; ++n) { const f32x4 cs = *(const f32x4*)(rr + 4 * n), sn = *(const f32x4*)(rr + 32 + 4 * n);
;                         const f32x4 x1 = x[0][n], x2 = x[1][n]; x[0][n] = x1 * cs - x2 * sn; x[1][n] = x1 * sn + x2 * cs; }
;                 }
; #pragma unroll
;                 for (int bj = 0; bj < 2; ++bj)
; #pragma unroll
;                     for (int n = 0; n < 2; ++n) x[bj][n] = x[bj][n] * qs;
;             }
; #pragma unroll
;             for (int bj = 0; bj < 2; ++bj) *(u32x4*)(dst + (size_t)r * ld + colb + 32 * bj + 8 * fq) = pk8(x[bj][0], x[bj][1]);
.LBB0_627:
	v_mad_i64_i32 v[192:193], s[10:11], s42, v200, 0
	v_lshl_add_u64 v[192:193], v[192:193], 1, v[98:99]
	v_cvt_pk_bf16_f32 v152, v152, v153
	v_cvt_pk_bf16_f32 v153, v154, v155
	v_cvt_pk_bf16_f32 v154, v148, v149
	v_cvt_pk_bf16_f32 v155, v150, v151
	v_cvt_pk_bf16_f32 v148, v156, v157
	v_cvt_pk_bf16_f32 v149, v158, v159
	v_cvt_pk_bf16_f32 v150, v160, v161
	v_cvt_pk_bf16_f32 v151, v162, v163
	v_add_u32_e32 v248, 0xa000, v251
	v_lshl_add_u64 v[252:253], v[176:177], 0, v[248:249]
	global_load_dwordx4 v[202:205], v[252:253], off offset:16
	global_load_dwordx4 v[206:209], v[252:253], off
	global_load_dwordx4 v[226:229], v[252:253], off offset:144
	global_load_dwordx4 v[230:233], v[252:253], off offset:128
	global_store_dwordx4 v[192:193], v[152:155], off
	global_store_dwordx4 v[192:193], v[148:151], off offset:64
	v_mov_b64_e32 v[158:159], v[18:19]
	v_mov_b64_e32 v[154:155], v[38:39]
	v_mov_b64_e32 v[150:151], v[30:31]
	v_mov_b64_e32 v[162:163], v[10:11]
	v_add_u32_e32 v200, 0xa0, v199
	s_and_b64 vcc, exec, s[8:9]
	v_mov_b64_e32 v[152:153], v[36:37]
	v_mov_b64_e32 v[148:149], v[28:29]
	v_mov_b64_e32 v[156:157], v[16:17]
	v_mov_b64_e32 v[160:161], v[8:9]
	s_cbranch_vccnz .LBB0_631
	v_pk_mul_f32 v[148:149], v[38:39], v[38:39]
	v_pk_mul_f32 v[150:151], v[36:37], v[36:37]
	v_mul_f32_e32 v96, v16, v16
	v_pk_mov_b32 v[152:153], v[150:151], v[148:149] op_sel:[1,0]
	v_mov_b32_e32 v151, v149
	v_pk_add_f32 v[148:149], v[152:153], v[150:151]
	v_pk_mul_f32 v[150:151], v[30:31], v[30:31]
	v_pk_mul_f32 v[152:153], v[28:29], v[28:29]
	v_pk_add_f32 v[148:149], v[148:149], v[148:149] op_sel_hi:[0,1]
	v_pk_mov_b32 v[154:155], v[152:153], v[150:151] op_sel:[1,0]
	v_mov_b32_e32 v153, v151
	v_pk_add_f32 v[150:151], v[154:155], v[152:153]
	v_pk_fma_f32 v[152:153], v[16:17], v[16:17], v[96:97] op_sel_hi:[1,1,0]
	v_mul_f32_e32 v96, v18, v18
	v_pk_add_f32 v[150:151], v[150:151], v[150:151] op_sel_hi:[0,1]
	v_pk_fma_f32 v[154:155], v[18:19], v[18:19], v[96:97] op_sel_hi:[1,1,0]
	v_mul_f32_e32 v152, v8, v8
	v_mul_f32_e32 v154, v9, v9
	v_mul_f32_e32 v150, v10, v10
	v_mul_f32_e32 v148, v11, v11
	v_pk_add_f32 v[152:153], v[152:153], v[154:155]
	v_pk_add_f32 v[148:149], v[150:151], v[148:149]
	s_nop 0
	v_pk_add_f32 v[148:149], v[152:153], v[148:149]
	s_nop 0
	v_add_f32_e32 v96, v148, v149
	ds_bpermute_b32 v148, v194, v96
	s_waitcnt lgkmcnt(0)
	v_add_f32_e32 v96, v96, v148
	ds_bpermute_b32 v148, v195, v96
	s_waitcnt lgkmcnt(0)
	v_add_f32_e32 v96, v96, v148
	v_fmamk_f32 v96, v96, 0x3c800000, v185
	v_mul_f32_e32 v148, 0x4f800000, v96
	v_cmp_gt_f32_e32 vcc, s65, v96
	s_nop 1
	v_cndmask_b32_e32 v96, v96, v148, vcc
	v_sqrt_f32_e32 v148, v96
	s_nop 0
	v_add_u32_e32 v149, -1, v148
	v_fma_f32 v150, -v149, v148, v96
	v_cmp_ge_f32_e64 s[12:13], 0, v150
	v_add_u32_e32 v150, 1, v148
	s_nop 0
	v_cndmask_b32_e64 v149, v148, v149, s[12:13]
	v_fma_f32 v148, -v150, v148, v96
	v_cmp_lt_f32_e64 s[12:13], 0, v148
	s_nop 1
	v_cndmask_b32_e64 v148, v149, v150, s[12:13]
	v_mul_f32_e32 v149, 0x37800000, v148
	v_cndmask_b32_e32 v148, v148, v149, vcc
	v_cmp_class_f32_e32 vcc, v96, v183
	s_nop 1
	v_cndmask_b32_e32 v96, v148, v96, vcc
	v_div_scale_f32 v148, s[10:11], v96, v96, 1.0
	v_rcp_f32_e32 v149, v148
	s_nop 0
	v_fma_f32 v150, -v148, v149, 1.0
	v_fmac_f32_e32 v149, v150, v149
	v_div_scale_f32 v150, vcc, 1.0, v96, 1.0
	v_mul_f32_e32 v151, v150, v149
	v_fma_f32 v152, -v148, v151, v150
	v_fmac_f32_e32 v151, v152, v149
	v_fma_f32 v148, -v148, v151, v150
	v_div_fmas_f32 v148, v148, v149, v151
	v_div_fixup_f32 v96, v148, v96, 1.0
	v_pk_mul_f32 v[148:149], v[36:37], v[96:97] op_sel_hi:[1,0]
	v_pk_mul_f32 v[150:151], v[38:39], v[96:97] op_sel_hi:[1,0]
	s_waitcnt vmcnt(2)
	v_pk_mul_f32 v[152:153], v[144:145], v[148:149]
	v_pk_mul_f32 v[154:155], v[146:147], v[150:151]
	v_pk_mul_f32 v[148:149], v[28:29], v[96:97] op_sel_hi:[1,0]
	v_pk_mul_f32 v[150:151], v[30:31], v[96:97] op_sel_hi:[1,0]
	v_pk_mul_f32 v[156:157], v[16:17], v[96:97] op_sel_hi:[1,0]
	v_pk_mul_f32 v[158:159], v[18:19], v[96:97] op_sel_hi:[1,0]
	v_pk_mul_f32 v[162:163], v[8:9], v[96:97] op_sel_hi:[1,0]
	v_pk_mul_f32 v[160:161], v[10:11], v[96:97] op_sel_hi:[1,0]
	v_pk_mul_f32 v[150:151], v[142:143], v[150:151]
	v_pk_mul_f32 v[148:149], v[140:141], v[148:149]
	v_pk_mul_f32 v[158:159], v[138:139], v[158:159]
	v_pk_mul_f32 v[156:157], v[136:137], v[156:157]
	v_pk_mul_f32 v[160:161], v[134:135], v[160:161]
	s_and_b64 vcc, exec, s[6:7]
	v_pk_mul_f32 v[192:193], v[132:133], v[162:163]
	s_cbranch_vccnz .LBB0_630
	v_pk_mul_f32 v[210:211], v[156:157], v[230:231]
	v_pk_mul_f32 v[162:163], v[158:159], v[232:233]
	v_pk_fma_f32 v[234:235], v[152:153], v[206:207], v[210:211] neg_lo:[0,0,1] neg_hi:[0,0,1]
	v_pk_mul_f32 v[152:153], v[152:153], v[230:231]
	v_pk_fma_f32 v[236:237], v[154:155], v[208:209], v[162:163] neg_lo:[0,0,1] neg_hi:[0,0,1]
	v_pk_mul_f32 v[154:155], v[154:155], v[232:233]
	v_pk_fma_f32 v[156:157], v[156:157], v[206:207], v[152:153]
	v_pk_mul_f32 v[152:153], v[160:161], v[228:229]
	v_pk_mul_f32 v[162:163], v[192:193], v[226:227]
	v_pk_fma_f32 v[158:159], v[158:159], v[208:209], v[154:155]
	v_pk_fma_f32 v[154:155], v[150:151], v[204:205], v[152:153] neg_lo:[0,0,1] neg_hi:[0,0,1]
	v_pk_fma_f32 v[152:153], v[148:149], v[202:203], v[162:163] neg_lo:[0,0,1] neg_hi:[0,0,1]
	v_pk_mul_f32 v[150:151], v[150:151], v[228:229]
	v_pk_mul_f32 v[148:149], v[148:149], v[226:227]
	v_pk_fma_f32 v[160:161], v[160:161], v[204:205], v[150:151]
	v_pk_fma_f32 v[192:193], v[192:193], v[202:203], v[148:149]
	v_mov_b64_e32 v[148:149], v[152:153]
	v_mov_b64_e32 v[150:151], v[154:155]
	v_mov_b64_e32 v[152:153], v[234:235]
	v_mov_b64_e32 v[154:155], v[236:237]
